# attention: per-segment priority toggles replaced by one static priority raise for the younger wave half (waves 4-7)
# speedup vs baseline: 1.0172x; 1.0172x over previous
.LBB0_32:
	s_setprio 0
	v_mov_b32_e32 v64, v209
	s_nop 1
	v_permlane32_swap_b32_e32 v209, v64
	v_add_f32_e32 v64, v209, v64
	v_div_scale_f32 v65, s[0:1], v64, v64, 1.0
	v_rcp_f32_e32 v66, v65
	s_lshl_b32 s70, s42, 8
	s_barrier
	v_fma_f32 v67, -v65, v66, 1.0
	v_fmac_f32_e32 v66, v67, v66
	v_div_scale_f32 v67, vcc, 1.0, v64, 1.0
	v_mul_f32_e32 v68, v67, v66
	v_fma_f32 v69, -v65, v68, v67
	v_fmac_f32_e32 v68, v69, v66
	v_fma_f32 v65, -v65, v68, v67
	v_div_fmas_f32 v65, v65, v66, v68
	v_lshlrev_b64 v[66:67], 11, v[206:207]
	v_div_fixup_f32 v64, v65, v64, 1.0
	v_readfirstlane_b32 s0, v206
	s_lshr_b32 s1, s25, 5
	v_mbcnt_lo_u32_b32 v70, -1, 0
	v_mbcnt_hi_u32_b32 v70, -1, v70
	s_mul_i32 s5, s1, 8704
	s_add_i32 s5, s5, 25600
	s_cmp_ge_u32 s1, 2
	s_cselect_b32 s7, 28672, 0
	s_add_i32 s5, s5, s7
	s_cmp_ge_u32 s1, 6
	s_cselect_b32 s7, 6144, 0
	s_add_i32 s5, s5, s7
	s_movk_i32 s7, 272
	v_and_b32_e32 v65, 31, v70
	v_mul_u32_u24_e32 v65, s7, v65
	v_lshl_add_u32 v65, v188, 1, v65
	v_add_u32_e32 v65, s5, v65
	v_lshrrev_b32_e32 v66, 4, v70
	v_and_b32_e32 v67, 15, v70
	v_mul_u32_u24_e32 v68, s7, v66
	v_lshl_add_u32 v68, v67, 4, v68
	v_add_u32_e32 v68, s5, v68
	v_add_u32_e32 v69, s0, v66
	v_lshlrev_b32_e32 v69, 11, v69
	v_lshl_add_u32 v69, v67, 4, v69
	v_add_u32_e32 v69, s70, v69
	v_pk_mul_f32 v[48:49], v[48:49], v[64:65] op_sel_hi:[1,0]
	v_pk_mul_f32 v[50:51], v[50:51], v[64:65] op_sel_hi:[1,0]
	v_pk_mul_f32 v[52:53], v[52:53], v[64:65] op_sel_hi:[1,0]
	v_pk_mul_f32 v[54:55], v[54:55], v[64:65] op_sel_hi:[1,0]
	v_pk_mul_f32 v[56:57], v[56:57], v[64:65] op_sel_hi:[1,0]
	v_pk_mul_f32 v[58:59], v[58:59], v[64:65] op_sel_hi:[1,0]
	v_pk_mul_f32 v[60:61], v[60:61], v[64:65] op_sel_hi:[1,0]
	v_pk_mul_f32 v[62:63], v[62:63], v[64:65] op_sel_hi:[1,0]
	v_pk_mul_f32 v[32:33], v[32:33], v[64:65] op_sel_hi:[1,0]
	v_pk_mul_f32 v[34:35], v[34:35], v[64:65] op_sel_hi:[1,0]
	v_pk_mul_f32 v[36:37], v[36:37], v[64:65] op_sel_hi:[1,0]
	v_pk_mul_f32 v[38:39], v[38:39], v[64:65] op_sel_hi:[1,0]
	v_pk_mul_f32 v[40:41], v[40:41], v[64:65] op_sel_hi:[1,0]
	v_pk_mul_f32 v[42:43], v[42:43], v[64:65] op_sel_hi:[1,0]
	v_pk_mul_f32 v[44:45], v[44:45], v[64:65] op_sel_hi:[1,0]
	v_pk_mul_f32 v[46:47], v[46:47], v[64:65] op_sel_hi:[1,0]
	v_pk_mul_f32 v[16:17], v[16:17], v[64:65] op_sel_hi:[1,0]
	v_pk_mul_f32 v[18:19], v[18:19], v[64:65] op_sel_hi:[1,0]
	v_pk_mul_f32 v[20:21], v[20:21], v[64:65] op_sel_hi:[1,0]
	v_pk_mul_f32 v[22:23], v[22:23], v[64:65] op_sel_hi:[1,0]
	v_pk_mul_f32 v[24:25], v[24:25], v[64:65] op_sel_hi:[1,0]
	v_pk_mul_f32 v[26:27], v[26:27], v[64:65] op_sel_hi:[1,0]
	v_pk_mul_f32 v[28:29], v[28:29], v[64:65] op_sel_hi:[1,0]
	v_pk_mul_f32 v[30:31], v[30:31], v[64:65] op_sel_hi:[1,0]
	v_pk_mul_f32 v[0:1], v[0:1], v[64:65] op_sel_hi:[1,0]
	v_pk_mul_f32 v[2:3], v[2:3], v[64:65] op_sel_hi:[1,0]
	v_pk_mul_f32 v[4:5], v[4:5], v[64:65] op_sel_hi:[1,0]
	v_pk_mul_f32 v[6:7], v[6:7], v[64:65] op_sel_hi:[1,0]
	v_pk_mul_f32 v[8:9], v[8:9], v[64:65] op_sel_hi:[1,0]
	v_pk_mul_f32 v[10:11], v[10:11], v[64:65] op_sel_hi:[1,0]
	v_pk_mul_f32 v[12:13], v[12:13], v[64:65] op_sel_hi:[1,0]
	v_pk_mul_f32 v[14:15], v[14:15], v[64:65] op_sel_hi:[1,0]
	v_cvt_pk_bf16_f32 v48, v48, v49
	v_cvt_pk_bf16_f32 v49, v50, v51
	v_cvt_pk_bf16_f32 v50, v52, v53
	v_cvt_pk_bf16_f32 v51, v54, v55
	v_cvt_pk_bf16_f32 v52, v56, v57
	v_cvt_pk_bf16_f32 v53, v58, v59
	v_cvt_pk_bf16_f32 v54, v60, v61
	v_cvt_pk_bf16_f32 v55, v62, v63
	v_cvt_pk_bf16_f32 v32, v32, v33
	v_cvt_pk_bf16_f32 v33, v34, v35
	v_cvt_pk_bf16_f32 v34, v36, v37
	v_cvt_pk_bf16_f32 v35, v38, v39
	v_cvt_pk_bf16_f32 v36, v40, v41
	v_cvt_pk_bf16_f32 v37, v42, v43
	v_cvt_pk_bf16_f32 v38, v44, v45
	v_cvt_pk_bf16_f32 v39, v46, v47
	v_cvt_pk_bf16_f32 v16, v16, v17
	v_cvt_pk_bf16_f32 v17, v18, v19
	v_cvt_pk_bf16_f32 v18, v20, v21
	v_cvt_pk_bf16_f32 v19, v22, v23
	v_cvt_pk_bf16_f32 v20, v24, v25
	v_cvt_pk_bf16_f32 v21, v26, v27
	v_cvt_pk_bf16_f32 v22, v28, v29
	v_cvt_pk_bf16_f32 v23, v30, v31
	v_cvt_pk_bf16_f32 v0, v0, v1
	v_cvt_pk_bf16_f32 v1, v2, v3
	v_cvt_pk_bf16_f32 v2, v4, v5
	v_cvt_pk_bf16_f32 v3, v6, v7
	v_cvt_pk_bf16_f32 v4, v8, v9
	v_cvt_pk_bf16_f32 v5, v10, v11
	v_cvt_pk_bf16_f32 v6, v12, v13
	v_cvt_pk_bf16_f32 v7, v14, v15
	ds_write_b64 v65, v[48:49] offset:0
	ds_write_b64 v65, v[50:51] offset:16
	ds_write_b64 v65, v[52:53] offset:32
	ds_write_b64 v65, v[54:55] offset:48
	ds_write_b64 v65, v[32:33] offset:64
	ds_write_b64 v65, v[34:35] offset:80
	ds_write_b64 v65, v[36:37] offset:96
	ds_write_b64 v65, v[38:39] offset:112
	s_waitcnt lgkmcnt(4)
	ds_write_b64 v65, v[16:17] offset:128
	ds_write_b64 v65, v[18:19] offset:144
	ds_write_b64 v65, v[20:21] offset:160
	ds_write_b64 v65, v[22:23] offset:176
	ds_write_b64 v65, v[0:1] offset:192
	ds_write_b64 v65, v[2:3] offset:208
	ds_write_b64 v65, v[4:5] offset:224
	ds_write_b64 v65, v[6:7] offset:240
	s_waitcnt lgkmcnt(0)
	ds_read_b128 v[72:75], v68 offset:0
	ds_read_b128 v[76:79], v68 offset:1088
	ds_read_b128 v[80:83], v68 offset:2176
	ds_read_b128 v[84:87], v68 offset:3264
	ds_read_b128 v[88:91], v68 offset:4352
	ds_read_b128 v[92:95], v68 offset:5440
	ds_read_b128 v[0:3], v68 offset:6528
	ds_read_b128 v[4:7], v68 offset:7616
	s_waitcnt lgkmcnt(7)
	global_store_dwordx4 v69, v[72:75], s[92:93]
	v_add_u32_e32 v69, 0x2000, v69
	s_waitcnt lgkmcnt(6)
	global_store_dwordx4 v69, v[76:79], s[92:93]
	v_add_u32_e32 v69, 0x2000, v69
	s_waitcnt lgkmcnt(5)
	global_store_dwordx4 v69, v[80:83], s[92:93]
	v_add_u32_e32 v69, 0x2000, v69
	s_waitcnt lgkmcnt(4)
	global_store_dwordx4 v69, v[84:87], s[92:93]
	v_add_u32_e32 v69, 0x2000, v69
	s_waitcnt lgkmcnt(3)
	global_store_dwordx4 v69, v[88:91], s[92:93]
	v_add_u32_e32 v69, 0x2000, v69
	s_waitcnt lgkmcnt(2)
	global_store_dwordx4 v69, v[92:95], s[92:93]
	v_add_u32_e32 v69, 0x2000, v69
	s_waitcnt lgkmcnt(1)
	global_store_dwordx4 v69, v[0:3], s[92:93]
	v_add_u32_e32 v69, 0x2000, v69
	s_waitcnt lgkmcnt(0)
	global_store_dwordx4 v69, v[4:7], s[92:93]
	v_readlane_b32 s0, v254, 7
	s_add_i32 s29, s29, s94
	s_add_i32 s28, s28, s0
	s_add_i32 s24, s24, s94
	s_cmpk_gt_i32 s29, 0x3ff
	v_readlane_b32 s1, v254, 8
	s_cbranch_scc1 .LBB0_52

.LatA_40:
	s_cmp_le_i32 s46, s44
	s_cselect_b64 s[0:1], -1, 0
	s_cbranch_scc0 .LatA_noqk
	s_and_b32 s5, s13, 1
	s_mul_i32 s7, s5, 0x6400
	v_add_u32_e32 v250, s7, v243
	ds_read_b128 v[166:169], v250
	ds_read_b128 v[172:175], v250 offset:12800
	ds_read_b128 v[176:179], v250 offset:32
	ds_read_b128 v[222:225], v250 offset:12832
	ds_read_b128 v[228:231], v250 offset:64
	ds_read_b128 v[232:235], v250 offset:12864
	s_waitcnt lgkmcnt(5)
	v_mfma_f32_32x32x16_bf16 v[64:79], v[166:169], v[132:135], 0
	ds_read_b128 v[166:169], v250 offset:96
	s_waitcnt lgkmcnt(5)
	v_mfma_f32_32x32x16_bf16 v[80:95], v[172:175], v[132:135], 0
	ds_read_b128 v[172:175], v250 offset:12896
	s_waitcnt lgkmcnt(5)
	v_mfma_f32_32x32x16_bf16 v[64:79], v[176:179], v[128:131], v[64:79]
	ds_read_b128 v[176:179], v250 offset:128
	s_waitcnt lgkmcnt(5)
	v_mfma_f32_32x32x16_bf16 v[80:95], v[222:225], v[128:131], v[80:95]
	ds_read_b128 v[222:225], v250 offset:12928
	s_waitcnt lgkmcnt(5)
	v_mfma_f32_32x32x16_bf16 v[64:79], v[228:231], v[124:127], v[64:79]
	ds_read_b128 v[228:231], v250 offset:160
	s_waitcnt lgkmcnt(5)
	v_mfma_f32_32x32x16_bf16 v[80:95], v[232:235], v[124:127], v[80:95]
	ds_read_b128 v[232:235], v250 offset:12960
	s_waitcnt lgkmcnt(5)
	v_mfma_f32_32x32x16_bf16 v[64:79], v[166:169], v[116:119], v[64:79]
	ds_read_b128 v[166:169], v250 offset:192
	s_waitcnt lgkmcnt(5)
	v_mfma_f32_32x32x16_bf16 v[80:95], v[172:175], v[116:119], v[80:95]
	ds_read_b128 v[172:175], v250 offset:12992
	s_waitcnt lgkmcnt(5)
	v_mfma_f32_32x32x16_bf16 v[64:79], v[176:179], v[112:115], v[64:79]
	ds_read_b128 v[176:179], v250 offset:224
	s_waitcnt lgkmcnt(5)
	v_mfma_f32_32x32x16_bf16 v[80:95], v[222:225], v[112:115], v[80:95]
	ds_read_b128 v[222:225], v250 offset:13024
	s_waitcnt lgkmcnt(5)
	v_mfma_f32_32x32x16_bf16 v[64:79], v[228:231], v[104:107], v[64:79]
	ds_read_b128 v[228:231], v250 offset:256
	s_waitcnt lgkmcnt(5)
	v_mfma_f32_32x32x16_bf16 v[80:95], v[232:235], v[104:107], v[80:95]
	ds_read_b128 v[232:235], v250 offset:13056
	s_waitcnt lgkmcnt(5)
	v_mfma_f32_32x32x16_bf16 v[64:79], v[166:169], v[100:103], v[64:79]
	ds_read_b128 v[166:169], v250 offset:288
	s_waitcnt lgkmcnt(5)
	v_mfma_f32_32x32x16_bf16 v[80:95], v[172:175], v[100:103], v[80:95]
	ds_read_b128 v[172:175], v250 offset:13088
	s_waitcnt lgkmcnt(5)
	v_mfma_f32_32x32x16_bf16 v[64:79], v[176:179], v[96:99], v[64:79]
	ds_read_b128 v[176:179], v250 offset:320
	s_waitcnt lgkmcnt(5)
	v_mfma_f32_32x32x16_bf16 v[80:95], v[222:225], v[96:99], v[80:95]
	ds_read_b128 v[222:225], v250 offset:13120
	s_waitcnt lgkmcnt(5)
	v_mfma_f32_32x32x16_bf16 v[64:79], v[228:231], v[120:123], v[64:79]
	ds_read_b128 v[228:231], v250 offset:352
	s_waitcnt lgkmcnt(5)
	v_mfma_f32_32x32x16_bf16 v[80:95], v[232:235], v[120:123], v[80:95]
	ds_read_b128 v[232:235], v250 offset:13152
	s_waitcnt lgkmcnt(5)
	v_mfma_f32_32x32x16_bf16 v[64:79], v[166:169], v[140:143], v[64:79]
	s_waitcnt lgkmcnt(4)
	v_mfma_f32_32x32x16_bf16 v[80:95], v[172:175], v[140:143], v[80:95]
	s_waitcnt lgkmcnt(3)
	v_mfma_f32_32x32x16_bf16 v[64:79], v[176:179], v[108:111], v[64:79]
	s_waitcnt lgkmcnt(2)
	v_mfma_f32_32x32x16_bf16 v[80:95], v[222:225], v[108:111], v[80:95]
	s_waitcnt lgkmcnt(1)
	v_mfma_f32_32x32x16_bf16 v[64:79], v[228:231], v[136:139], v[64:79]
	s_waitcnt lgkmcnt(0)
	v_mfma_f32_32x32x16_bf16 v[80:95], v[232:235], v[136:139], v[80:95]

.LatB_pre:
	s_setprio 1

.LatB_noprev:
	s_cmp_le_i32 s46, s44
	s_cbranch_scc0 .LatB_noqk
	s_and_b32 s5, s13, 1
	s_mul_i32 s7, s5, 0x6400
	v_add_u32_e32 v250, s7, v243
	ds_read_b128 v[166:169], v250
	ds_read_b128 v[172:175], v250 offset:12800
	ds_read_b128 v[176:179], v250 offset:32
	ds_read_b128 v[222:225], v250 offset:12832
	ds_read_b128 v[228:231], v250 offset:64
	ds_read_b128 v[232:235], v250 offset:12864
	s_waitcnt lgkmcnt(5)
	v_mfma_f32_32x32x16_bf16 v[64:79], v[166:169], v[132:135], 0
	ds_read_b128 v[166:169], v250 offset:96
	s_waitcnt lgkmcnt(5)
	v_mfma_f32_32x32x16_bf16 v[80:95], v[172:175], v[132:135], 0
	ds_read_b128 v[172:175], v250 offset:12896
	s_waitcnt lgkmcnt(5)
	v_mfma_f32_32x32x16_bf16 v[64:79], v[176:179], v[128:131], v[64:79]
	ds_read_b128 v[176:179], v250 offset:128
	s_waitcnt lgkmcnt(5)
	v_mfma_f32_32x32x16_bf16 v[80:95], v[222:225], v[128:131], v[80:95]
	ds_read_b128 v[222:225], v250 offset:12928
	s_waitcnt lgkmcnt(5)
	v_mfma_f32_32x32x16_bf16 v[64:79], v[228:231], v[124:127], v[64:79]
	ds_read_b128 v[228:231], v250 offset:160
	s_waitcnt lgkmcnt(5)
	v_mfma_f32_32x32x16_bf16 v[80:95], v[232:235], v[124:127], v[80:95]
	ds_read_b128 v[232:235], v250 offset:12960
	s_waitcnt lgkmcnt(5)
	v_mfma_f32_32x32x16_bf16 v[64:79], v[166:169], v[116:119], v[64:79]
	ds_read_b128 v[166:169], v250 offset:192
	s_waitcnt lgkmcnt(5)
	v_mfma_f32_32x32x16_bf16 v[80:95], v[172:175], v[116:119], v[80:95]
	ds_read_b128 v[172:175], v250 offset:12992
	s_waitcnt lgkmcnt(5)
	v_mfma_f32_32x32x16_bf16 v[64:79], v[176:179], v[112:115], v[64:79]
	ds_read_b128 v[176:179], v250 offset:224
	s_waitcnt lgkmcnt(5)
	v_mfma_f32_32x32x16_bf16 v[80:95], v[222:225], v[112:115], v[80:95]
	ds_read_b128 v[222:225], v250 offset:13024
	s_waitcnt lgkmcnt(5)
	v_mfma_f32_32x32x16_bf16 v[64:79], v[228:231], v[104:107], v[64:79]
	ds_read_b128 v[228:231], v250 offset:256
	s_waitcnt lgkmcnt(5)
	v_mfma_f32_32x32x16_bf16 v[80:95], v[232:235], v[104:107], v[80:95]
	ds_read_b128 v[232:235], v250 offset:13056
	s_waitcnt lgkmcnt(5)
	v_mfma_f32_32x32x16_bf16 v[64:79], v[166:169], v[100:103], v[64:79]
	ds_read_b128 v[166:169], v250 offset:288
	s_waitcnt lgkmcnt(5)
	v_mfma_f32_32x32x16_bf16 v[80:95], v[172:175], v[100:103], v[80:95]
	ds_read_b128 v[172:175], v250 offset:13088
	s_waitcnt lgkmcnt(5)
	v_mfma_f32_32x32x16_bf16 v[64:79], v[176:179], v[96:99], v[64:79]
	ds_read_b128 v[176:179], v250 offset:320
	s_waitcnt lgkmcnt(5)
	v_mfma_f32_32x32x16_bf16 v[80:95], v[222:225], v[96:99], v[80:95]
	ds_read_b128 v[222:225], v250 offset:13120
	s_waitcnt lgkmcnt(5)
	v_mfma_f32_32x32x16_bf16 v[64:79], v[228:231], v[120:123], v[64:79]
	ds_read_b128 v[228:231], v250 offset:352
	s_waitcnt lgkmcnt(5)
	v_mfma_f32_32x32x16_bf16 v[80:95], v[232:235], v[120:123], v[80:95]
	ds_read_b128 v[232:235], v250 offset:13152
	s_waitcnt lgkmcnt(5)
	v_mfma_f32_32x32x16_bf16 v[64:79], v[166:169], v[140:143], v[64:79]
	s_waitcnt lgkmcnt(4)
	v_mfma_f32_32x32x16_bf16 v[80:95], v[172:175], v[140:143], v[80:95]
	s_waitcnt lgkmcnt(3)
	v_mfma_f32_32x32x16_bf16 v[64:79], v[176:179], v[108:111], v[64:79]
	s_waitcnt lgkmcnt(2)
	v_mfma_f32_32x32x16_bf16 v[80:95], v[222:225], v[108:111], v[80:95]
	s_waitcnt lgkmcnt(1)
	v_mfma_f32_32x32x16_bf16 v[64:79], v[228:231], v[136:139], v[64:79]
	s_waitcnt lgkmcnt(0)
	v_mfma_f32_32x32x16_bf16 v[80:95], v[232:235], v[136:139], v[80:95]
